# norm phases: per-iteration s_waitcnt vmcnt(0) -> counted vmcnt(24) waits in steady iterations (three rows stay in flight)
# baseline (speedup 1.0000x reference)
; template <int MODE> __device__ __forceinline__ void norm_phase(unsigned char* ws, float* out, const float* gpost, const bf16* mbuf, int G) {
;     ...
;     NRow<MODE> A, B, C, D;
;     int r = gw;
;     if (r < MTOT) norm_load<MODE>(A, ws, mbuf, r, lane);
;     if (r + NGW < MTOT) norm_load<MODE>(B, ws, mbuf, r + NGW, lane);
;     if (r + 2 * NGW < MTOT) norm_load<MODE>(C, ws, mbuf, r + 2 * NGW, lane);
;     for (; r < MTOT; r += 4 * NGW) {
;         const int r1 = r + NGW, r2 = r1 + NGW, r3 = r2 + NGW, r4 = r3 + NGW, r5 = r4 + NGW, r6 = r5 + NGW;
;         if (r3 < MTOT) norm_load<MODE>(D, ws, mbuf, r3, lane);
;         norm_process<MODE>(A, ws, out, r, lane, gp);
;         if (r4 < MTOT) norm_load<MODE>(A, ws, mbuf, r4, lane);
;         if (r1 < MTOT) norm_process<MODE>(B, ws, out, r1, lane, gp);
;         if (r5 < MTOT) norm_load<MODE>(B, ws, mbuf, r5, lane);
;         if (r2 < MTOT) norm_process<MODE>(C, ws, out, r2, lane, gp);
;         if (r6 < MTOT) norm_load<MODE>(C, ws, mbuf, r6, lane);
;         if (r3 < MTOT) norm_process<MODE>(D, ws, out, r3, lane, gp);
;     }
.LBB0_207:
	s_or_b64 exec, exec, s[2:3]
	s_and_saveexec_b64 s[28:29], vcc
	s_cbranch_execz .LBB0_229
	v_mov_b32_e32 v71, v0
	v_lshl_add_u64 v[14:15], s[20:21], 0, v[70:71]
	v_lshl_add_u64 v[86:87], s[6:7], 0, v[70:71]
	v_lshlrev_b32_e32 v70, 4, v73
	v_readlane_b32 s2, v244, 15
	v_and_b32_e32 v73, 0x3f0, v70
	v_lshlrev_b64 v[90:91], 11, v[104:105]
	v_add_u32_e32 v70, s2, v72
	v_ashrrev_i32_e32 v71, 31, v70
	v_readlane_b32 s2, v244, 16
	v_lshl_add_u64 v[92:93], v[70:71], 2, v[182:183]
	v_lshlrev_b64 v[94:95], 11, v[70:71]
	v_add_u32_e32 v70, s2, v72
	v_ashrrev_i32_e32 v71, 31, v70
	v_readlane_b32 s2, v244, 17
	v_lshl_add_u64 v[96:97], v[70:71], 2, v[182:183]
	v_lshlrev_b64 v[98:99], 11, v[70:71]
	v_add_u32_e32 v70, s2, v72
	v_ashrrev_i32_e32 v71, 31, v70
	v_lshlrev_b64 v[102:103], 11, v[70:71]
	v_cmp_eq_u32_e64 s[0:1], 0, v74
	v_lshl_add_u64 v[88:89], v[104:105], 2, v[182:183]
	v_or_b32_e32 v90, v90, v73
	v_or_b32_e32 v94, v94, v73
	v_or_b32_e32 v98, v98, v73
	v_lshl_add_u64 v[100:101], v[70:71], 2, v[182:183]
	v_or_b32_e32 v102, v102, v73
	s_mov_b64 s[46:47], 0
	s_mov_b32 s2, 1
	s_nop 0
	v_writelane_b32 v246, s2, 3
	s_branch .LBB0_210
.LBB0_209:
	s_mov_b32 s2, 0
	s_nop 0
	v_writelane_b32 v246, s2, 3
	s_or_b64 exec, exec, s[50:51]
	s_and_b64 s[2:3], exec, vcc
	s_or_b64 s[46:47], s[2:3], s[46:47]
	v_lshl_add_u64 v[88:89], v[88:89], 0, s[96:97]
	v_lshl_add_u64 v[90:91], v[90:91], 0, s[98:99]
	v_lshl_add_u64 v[92:93], v[92:93], 0, s[96:97]
	v_lshl_add_u64 v[94:95], v[94:95], 0, s[98:99]
	v_lshl_add_u64 v[96:97], v[96:97], 0, s[96:97]
	v_lshl_add_u64 v[98:99], v[98:99], 0, s[98:99]
	v_lshl_add_u64 v[100:101], v[100:101], 0, s[96:97]
	v_lshl_add_u64 v[102:103], v[102:103], 0, s[98:99]
	s_andn2_b64 exec, exec, s[46:47]
	s_cbranch_execz .LBB0_229
.LBB0_210:
	v_mov_b32_e32 v112, v104
	s_mul_i32 s2, s33, 48
	v_add_u32_e32 v247, s2, v112
	v_cmp_gt_i32_e32 vcc, s63, v247
	v_readlane_b32 s2, v246, 3
	s_or_b32 s3, vcc_lo, vcc_hi
	s_cmp_eq_u32 s2, 0
	s_cselect_b32 s3, s3, 0
	s_nop 0
	v_writelane_b32 v246, s3, 4
	s_mul_i32 s2, s33, 24
	v_add_u32_e32 v104, s2, v112
	v_cmp_gt_i32_e64 s[4:5], s63, v104
	v_lshl_add_u64 v[106:107], s[14:15], 0, v[102:103]
	s_and_saveexec_b64 s[2:3], s[4:5]
	s_cbranch_execz .LBB0_212
	v_add_co_u32_e32 v74, vcc, 0x1e000000, v106
	v_lshl_add_u64 v[104:105], s[14:15], 0, v[100:101]
	s_nop 0
	v_addc_co_u32_e32 v75, vcc, 0, v107, vcc
	v_add_co_u32_e32 v82, vcc, 0x6000000, v106
	global_load_dwordx4 v[70:73], v[74:75], off nt
	s_nop 0
	global_load_dwordx4 v[74:77], v[74:75], off offset:1024 nt
	v_addc_co_u32_e32 v83, vcc, 0, v107, vcc
	global_load_dwordx4 v[78:81], v[82:83], off
	s_nop 0
	global_load_dwordx4 v[82:85], v[82:83], off offset:1024
	s_nop 0
	global_load_dword v111, v[104:105], off
.LBB0_212:
	s_or_b64 exec, exec, s[2:3]
	v_readlane_b32 s2, v246, 4
	s_nop 0
	s_cmp_lg_u32 s2, 0
	s_cbranch_scc1 .Lna_mid_1
	s_waitcnt vmcnt(0)
	s_branch .Lna_done_1
.Lna_mid_1:
	s_waitcnt vmcnt(24)
; __device__ __forceinline__ unsigned cvtpk(float lo, float hi) { unsigned r; asm volatile("v_cvt_pk_bf16_f32 %0, %1, %2" : "=v"(r) : "v"(lo), "v"(hi)); return r; }
; __device__ __forceinline__ float bf_lo(unsigned w) { return __uint_as_float(w << 16); }
; __device__ __forceinline__ float bf_hi(unsigned w) { return __uint_as_float(w & 0xffff0000u); }
; template <int MODE> __device__ __forceinline__ void norm_process(const NRow<MODE>& R, unsigned char* ws, float* out, int r, int lane, const float (&gp)[2][8]) {
;     float mf[2][8], xv[2][8]; float s = 0.f;
; #pragma unroll
;     for (int j = 0; j < 2; ++j) {
; #pragma unroll
;         for (int i = 0; i < 4; ++i) { mf[j][2 * i] = bf_lo(R.m[j][i]); mf[j][2 * i + 1] = bf_hi(R.m[j][i]); }
;         { const float ir = __builtin_amdgcn_rcpf(R.rs);
; #pragma unroll
;             for (int i = 0; i < 4; ++i) { xv[j][2 * i] = bf_lo(R.xh[j][i]) * ir; xv[j][2 * i + 1] = bf_hi(R.xh[j][i]) * ir; } }
; #pragma unroll
;         for (int i = 0; i < 8; ++i) s += mf[j][i] * mf[j][i]; }
;     const float rstd = __builtin_amdgcn_rsqf(wave_sum(s) * (1.f / DM) + RMS_EPS);
;     float s2 = 0.f;
; #pragma unroll
;     for (int j = 0; j < 2; ++j)
; #pragma unroll
;         for (int i = 0; i < 8; ++i) { xv[j][i] += mf[j][i] * rstd * gp[j][i]; s2 += xv[j][i] * xv[j][i]; }
;     if (MODE == 2) { float* orow = out + (size_t)r * DM + 8 * lane;
; #pragma unroll
;         for (int j = 0; j < 2; ++j) { __builtin_nontemporal_store((f32x4){xv[j][0], xv[j][1], xv[j][2], xv[j][3]}, (f32x4*)(orow + 512 * j)); __builtin_nontemporal_store((f32x4){xv[j][4], xv[j][5], xv[j][6], xv[j][7]}, (f32x4*)(orow + 512 * j + 4)); } }
;     else {
;         const float rstd2 = __builtin_amdgcn_rsqf(wave_sum(s2) * (1.f / DM) + RMS_EPS);
;         bf16* xo = (bf16*)(ws + WS_XN) + (size_t)r * DM + 8 * lane;
; #pragma unroll
;         for (int j = 0; j < 2; ++j) { u32x4 a;
; #pragma unroll
;             for (int i = 0; i < 4; ++i) a[i] = cvtpk(xv[j][2 * i] * rstd2, xv[j][2 * i + 1] * rstd2);
;             *(u32x4*)(xo + 512 * j) = a; }
;         if (lane == 0) ((float*)(ws + WS_RSTD))[r] = rstd2; }
.Lna_done_1:
	v_lshlrev_b32_e32 v125, 16, v22
	v_and_b32_e32 v127, 0xffff0000, v22
	v_mul_f32_e32 v105, v125, v125
	v_lshlrev_b32_e32 v121, 16, v23
	v_fmac_f32_e32 v105, v127, v127
	v_and_b32_e32 v123, 0xffff0000, v23
	v_fmac_f32_e32 v105, v121, v121
	v_lshlrev_b32_e32 v117, 16, v24
	v_fmac_f32_e32 v105, v123, v123
	v_and_b32_e32 v119, 0xffff0000, v24
	v_fmac_f32_e32 v105, v117, v117
	v_lshlrev_b32_e32 v109, 16, v25
	v_fmac_f32_e32 v105, v119, v119
	v_and_b32_e32 v115, 0xffff0000, v25
	v_fmac_f32_e32 v105, v109, v109
	v_lshlrev_b32_e32 v141, 16, v26
	v_fmac_f32_e32 v105, v115, v115
	v_and_b32_e32 v143, 0xffff0000, v26
	v_fmac_f32_e32 v105, v141, v141
	v_lshlrev_b32_e32 v137, 16, v27
	v_fmac_f32_e32 v105, v143, v143
	v_and_b32_e32 v139, 0xffff0000, v27
	v_fmac_f32_e32 v105, v137, v137
	v_lshlrev_b32_e32 v133, 16, v28
	v_fmac_f32_e32 v105, v139, v139
	v_and_b32_e32 v135, 0xffff0000, v28
	v_fmac_f32_e32 v105, v133, v133
	v_lshlrev_b32_e32 v129, 16, v29
	v_fmac_f32_e32 v105, v135, v135
	v_and_b32_e32 v131, 0xffff0000, v29
	v_fmac_f32_e32 v105, v129, v129
	v_fmac_f32_e32 v105, v131, v131
	v_rcp_f32_e32 v104, v1
	v_and_b32_e32 v126, 0xffff0000, v30
	v_add_f32_dpp v105, v105, v105 quad_perm:[1,0,3,2] row_mask:0xf bank_mask:0xf bound_ctrl:1
	v_lshlrev_b32_e32 v124, 16, v30
	v_lshlrev_b32_e32 v120, 16, v31
	v_add_f32_dpp v105, v105, v105 quad_perm:[2,3,0,1] row_mask:0xf bank_mask:0xf bound_ctrl:1
	v_and_b32_e32 v122, 0xffff0000, v31
	v_lshlrev_b32_e32 v116, 16, v32
	v_add_f32_dpp v105, v105, v105 row_half_mirror row_mask:0xf bank_mask:0xf bound_ctrl:1
	v_and_b32_e32 v118, 0xffff0000, v32
	v_lshlrev_b32_e32 v108, 16, v33
	v_add_f32_dpp v105, v105, v105 row_mirror row_mask:0xf bank_mask:0xf bound_ctrl:1
	v_mov_b32_e32 v113, v105
	s_nop 1
	v_permlane16_swap_b32_e32 v105, v113
	v_add_f32_e32 v105, v105, v113
	v_mov_b32_e32 v113, v105
	s_nop 1
	v_permlane32_swap_b32_e32 v105, v113
	v_add_f32_e32 v105, v105, v113
	v_fmamk_f32 v105, v105, 0x3a800000, v201
	v_rsq_f32_e32 v105, v105
	v_and_b32_e32 v114, 0xffff0000, v33
	v_lshlrev_b32_e32 v140, 16, v34
	v_and_b32_e32 v142, 0xffff0000, v34
	v_pk_mul_f32 v[126:127], v[104:105], v[126:127]
	v_pk_mul_f32 v[124:125], v[104:105], v[124:125]
	v_fmac_f32_e32 v126, v7, v127
	v_fmac_f32_e32 v124, v6, v125
	v_mul_f32_e32 v113, v126, v126
	v_pk_mul_f32 v[120:121], v[104:105], v[120:121]
	v_fmac_f32_e32 v113, v124, v124
	v_fmac_f32_e32 v120, v8, v121
	v_pk_mul_f32 v[122:123], v[104:105], v[122:123]
	v_fmac_f32_e32 v113, v120, v120
	v_fmac_f32_e32 v122, v9, v123
	v_pk_mul_f32 v[116:117], v[104:105], v[116:117]
	v_fmac_f32_e32 v113, v122, v122
	v_fmac_f32_e32 v116, v2, v117
	v_pk_mul_f32 v[118:119], v[104:105], v[118:119]
	v_fmac_f32_e32 v113, v116, v116
	v_fmac_f32_e32 v118, v3, v119
	v_pk_mul_f32 v[108:109], v[104:105], v[108:109]
	v_fmac_f32_e32 v113, v118, v118
	v_fmac_f32_e32 v108, v4, v109
	v_pk_mul_f32 v[144:145], v[104:105], v[114:115]
	v_fmac_f32_e32 v113, v108, v108
	v_fmac_f32_e32 v144, v5, v145
	v_pk_mul_f32 v[140:141], v[104:105], v[140:141]
	v_lshlrev_b32_e32 v136, 16, v35
	v_fmac_f32_e32 v113, v144, v144
	v_fmac_f32_e32 v140, v18, v141
	v_pk_mul_f32 v[142:143], v[104:105], v[142:143]
	v_and_b32_e32 v138, 0xffff0000, v35
	v_fmac_f32_e32 v113, v140, v140
	v_fmac_f32_e32 v142, v19, v143
	v_pk_mul_f32 v[136:137], v[104:105], v[136:137]
	v_lshlrev_b32_e32 v132, 16, v36
	v_fmac_f32_e32 v113, v142, v142
	v_fmac_f32_e32 v136, v20, v137
	v_pk_mul_f32 v[138:139], v[104:105], v[138:139]
	v_and_b32_e32 v134, 0xffff0000, v36
	v_fmac_f32_e32 v113, v136, v136
	v_fmac_f32_e32 v138, v21, v139
	v_pk_mul_f32 v[132:133], v[104:105], v[132:133]
	v_lshlrev_b32_e32 v128, 16, v37
	v_fmac_f32_e32 v113, v138, v138
	v_fmac_f32_e32 v132, v10, v133
	v_pk_mul_f32 v[134:135], v[104:105], v[134:135]
	v_and_b32_e32 v130, 0xffff0000, v37
	v_fmac_f32_e32 v113, v132, v132
	v_fmac_f32_e32 v134, v11, v135
	v_pk_mul_f32 v[128:129], v[104:105], v[128:129]
	v_fmac_f32_e32 v113, v134, v134
	v_fmac_f32_e32 v128, v12, v129
	v_pk_mul_f32 v[130:131], v[104:105], v[130:131]
	v_fmac_f32_e32 v113, v128, v128
	v_fmac_f32_e32 v130, v13, v131
	v_fmac_f32_e32 v113, v130, v130
	v_lshl_add_u64 v[146:147], s[14:15], 0, v[90:91]
	s_nop 0
	v_add_f32_dpp v104, v113, v113 quad_perm:[1,0,3,2] row_mask:0xf bank_mask:0xf bound_ctrl:1
	s_nop 1
	v_add_f32_dpp v104, v104, v104 quad_perm:[2,3,0,1] row_mask:0xf bank_mask:0xf bound_ctrl:1
	s_nop 1
	v_add_f32_dpp v104, v104, v104 row_half_mirror row_mask:0xf bank_mask:0xf bound_ctrl:1
	s_nop 1
	v_add_f32_dpp v104, v104, v104 row_mirror row_mask:0xf bank_mask:0xf bound_ctrl:1
	v_mov_b32_e32 v105, v104
	s_nop 1
	v_permlane16_swap_b32_e32 v104, v105
	v_add_f32_e32 v104, v104, v105
	v_mov_b32_e32 v105, v104
	s_nop 1
	v_permlane32_swap_b32_e32 v104, v105
	v_add_f32_e32 v104, v104, v105
	v_fmamk_f32 v104, v104, 0x3a800000, v201
	v_rsq_f32_e32 v104, v104
	s_nop 0
	v_mul_f32_e32 v105, v124, v104
	v_mul_f32_e32 v109, v126, v104
	v_cvt_pk_bf16_f32 v114, v105, v109
	v_mul_f32_e32 v105, v120, v104
	v_mul_f32_e32 v109, v122, v104
	v_cvt_pk_bf16_f32 v115, v105, v109
	v_mul_f32_e32 v105, v116, v104
	v_mul_f32_e32 v109, v118, v104
	v_cvt_pk_bf16_f32 v116, v105, v109
	v_mul_f32_e32 v105, v108, v104
	v_mul_f32_e32 v108, v144, v104
	v_cvt_pk_bf16_f32 v117, v105, v108
	v_add_co_u32_e32 v108, vcc, s65, v146
	v_mul_f32_e32 v105, v140, v104
	s_nop 0
	v_addc_co_u32_e32 v109, vcc, 0, v147, vcc
	v_mul_f32_e32 v113, v142, v104
	global_store_dwordx4 v[108:109], v[114:117], off
	s_nop 1
	v_cvt_pk_bf16_f32 v114, v105, v113
	v_mul_f32_e32 v105, v136, v104
	v_mul_f32_e32 v113, v138, v104
	v_cvt_pk_bf16_f32 v115, v105, v113
	v_mul_f32_e32 v105, v132, v104
	v_mul_f32_e32 v113, v134, v104
	v_cvt_pk_bf16_f32 v116, v105, v113
	v_mul_f32_e32 v105, v128, v104
	v_mul_f32_e32 v113, v130, v104
	v_cvt_pk_bf16_f32 v117, v105, v113
	global_store_dwordx4 v[108:109], v[114:117], off offset:1024
	s_and_saveexec_b64 s[2:3], s[0:1]
	s_cbranch_execz .LBB0_214
	v_lshl_add_u64 v[108:109], s[14:15], 0, v[88:89]
	global_store_dword v[108:109], v104, off

; __device__ __forceinline__ unsigned cvtpk(float lo, float hi) { unsigned r; asm volatile("v_cvt_pk_bf16_f32 %0, %1, %2" : "=v"(r) : "v"(lo), "v"(hi)); return r; }
; __device__ __forceinline__ float bf_lo(unsigned w) { return __uint_as_float(w << 16); }
; __device__ __forceinline__ float bf_hi(unsigned w) { return __uint_as_float(w & 0xffff0000u); }
; template <int MODE> __device__ __forceinline__ void norm_process(const NRow<MODE>& R, unsigned char* ws, float* out, int r, int lane, const float (&gp)[2][8]) {
;     float mf[2][8], xv[2][8]; float s = 0.f;
; #pragma unroll
;     for (int j = 0; j < 2; ++j) {
; #pragma unroll
;         for (int i = 0; i < 4; ++i) { mf[j][2 * i] = bf_lo(R.m[j][i]); mf[j][2 * i + 1] = bf_hi(R.m[j][i]); }
;         { const float ir = __builtin_amdgcn_rcpf(R.rs);
; #pragma unroll
;             for (int i = 0; i < 4; ++i) { xv[j][2 * i] = bf_lo(R.xh[j][i]) * ir; xv[j][2 * i + 1] = bf_hi(R.xh[j][i]) * ir; } }
; #pragma unroll
;         for (int i = 0; i < 8; ++i) s += mf[j][i] * mf[j][i]; }
;     const float rstd = __builtin_amdgcn_rsqf(wave_sum(s) * (1.f / DM) + RMS_EPS);
;     float s2 = 0.f;
; #pragma unroll
;     for (int j = 0; j < 2; ++j)
; #pragma unroll
;         for (int i = 0; i < 8; ++i) { xv[j][i] += mf[j][i] * rstd * gp[j][i]; s2 += xv[j][i] * xv[j][i]; }
;     if (MODE == 2) { float* orow = out + (size_t)r * DM + 8 * lane;
; #pragma unroll
;         for (int j = 0; j < 2; ++j) { __builtin_nontemporal_store((f32x4){xv[j][0], xv[j][1], xv[j][2], xv[j][3]}, (f32x4*)(orow + 512 * j)); __builtin_nontemporal_store((f32x4){xv[j][4], xv[j][5], xv[j][6], xv[j][7]}, (f32x4*)(orow + 512 * j + 4)); } }
;     else {
;         const float rstd2 = __builtin_amdgcn_rsqf(wave_sum(s2) * (1.f / DM) + RMS_EPS);
;         bf16* xo = (bf16*)(ws + WS_XN) + (size_t)r * DM + 8 * lane;
; #pragma unroll
;         for (int j = 0; j < 2; ++j) { u32x4 a;
; #pragma unroll
;             for (int i = 0; i < 4; ++i) a[i] = cvtpk(xv[j][2 * i] * rstd2, xv[j][2 * i + 1] * rstd2);
;             *(u32x4*)(xo + 512 * j) = a; }
;         if (lane == 0) ((float*)(ws + WS_RSTD))[r] = rstd2; }
; template <int MODE> __device__ __forceinline__ void norm_phase(unsigned char* ws, float* out, const float* gpost, const bf16* mbuf, int G) {
;     ...
;         if (r1 < MTOT) norm_process<MODE>(B, ws, out, r1, lane, gp);
.LBB0_216:
	s_or_b64 exec, exec, s[50:51]
	v_add_u32_e32 v105, s57, v112
	v_cmp_gt_i32_e64 s[2:3], s63, v105
	s_and_saveexec_b64 s[50:51], s[2:3]
	s_cbranch_execz .LBB0_219
	v_readlane_b32 s2, v246, 4
	s_nop 0
	s_cmp_lg_u32 s2, 0
	s_cbranch_scc0 .Lna_skip_2
	s_waitcnt vmcnt(24)
.Lna_skip_2:
	v_lshlrev_b32_e32 v127, 16, v38
	v_and_b32_e32 v129, 0xffff0000, v38
	v_mul_f32_e32 v105, v127, v127
	v_lshlrev_b32_e32 v123, 16, v39
	v_fmac_f32_e32 v105, v129, v129
	v_and_b32_e32 v125, 0xffff0000, v39
	v_fmac_f32_e32 v105, v123, v123
	v_lshlrev_b32_e32 v119, 16, v40
	v_fmac_f32_e32 v105, v125, v125
	v_and_b32_e32 v121, 0xffff0000, v40
	v_fmac_f32_e32 v105, v119, v119
	v_lshlrev_b32_e32 v115, 16, v41
	v_fmac_f32_e32 v105, v121, v121
	v_and_b32_e32 v117, 0xffff0000, v41
	v_fmac_f32_e32 v105, v115, v115
	v_lshlrev_b32_e32 v143, 16, v42
	v_fmac_f32_e32 v105, v117, v117
	v_and_b32_e32 v145, 0xffff0000, v42
	v_fmac_f32_e32 v105, v143, v143
	v_lshlrev_b32_e32 v139, 16, v43
	v_fmac_f32_e32 v105, v145, v145
	v_and_b32_e32 v141, 0xffff0000, v43
	v_fmac_f32_e32 v105, v139, v139
	v_lshlrev_b32_e32 v135, 16, v44
	v_fmac_f32_e32 v105, v141, v141
	v_and_b32_e32 v137, 0xffff0000, v44
	v_fmac_f32_e32 v105, v135, v135
	v_lshlrev_b32_e32 v131, 16, v45
	v_fmac_f32_e32 v105, v137, v137
	v_and_b32_e32 v133, 0xffff0000, v45
	v_fmac_f32_e32 v105, v131, v131
	v_fmac_f32_e32 v105, v133, v133
	v_rcp_f32_e32 v108, v17
	v_and_b32_e32 v128, 0xffff0000, v46
	v_add_f32_dpp v105, v105, v105 quad_perm:[1,0,3,2] row_mask:0xf bank_mask:0xf bound_ctrl:1
	v_lshlrev_b32_e32 v126, 16, v46
	v_lshlrev_b32_e32 v122, 16, v47
	v_add_f32_dpp v105, v105, v105 quad_perm:[2,3,0,1] row_mask:0xf bank_mask:0xf bound_ctrl:1
	v_and_b32_e32 v124, 0xffff0000, v47
	v_lshlrev_b32_e32 v118, 16, v48
	v_add_f32_dpp v105, v105, v105 row_half_mirror row_mask:0xf bank_mask:0xf bound_ctrl:1
	v_and_b32_e32 v120, 0xffff0000, v48
	v_lshlrev_b32_e32 v114, 16, v49
	v_add_f32_dpp v105, v105, v105 row_mirror row_mask:0xf bank_mask:0xf bound_ctrl:1
	v_mov_b32_e32 v109, v105
	s_nop 1
	v_permlane16_swap_b32_e32 v105, v109
	v_add_f32_e32 v105, v105, v109
	v_mov_b32_e32 v109, v105
	s_nop 1
	v_permlane32_swap_b32_e32 v105, v109
	v_add_f32_e32 v105, v105, v109
	v_fmamk_f32 v105, v105, 0x3a800000, v201
	v_rsq_f32_e32 v109, v105
	v_and_b32_e32 v116, 0xffff0000, v49
	v_lshlrev_b32_e32 v142, 16, v50
	v_and_b32_e32 v144, 0xffff0000, v50
	v_pk_mul_f32 v[128:129], v[108:109], v[128:129]
	v_pk_mul_f32 v[126:127], v[108:109], v[126:127]
	v_fmac_f32_e32 v128, v7, v129
	v_fmac_f32_e32 v126, v6, v127
	v_mul_f32_e32 v105, v128, v128
	v_pk_mul_f32 v[122:123], v[108:109], v[122:123]
	v_fmac_f32_e32 v105, v126, v126
	v_fmac_f32_e32 v122, v8, v123
	v_pk_mul_f32 v[124:125], v[108:109], v[124:125]
	v_fmac_f32_e32 v105, v122, v122
	v_fmac_f32_e32 v124, v9, v125
	v_pk_mul_f32 v[118:119], v[108:109], v[118:119]
	v_fmac_f32_e32 v105, v124, v124
	v_fmac_f32_e32 v118, v2, v119
	v_pk_mul_f32 v[120:121], v[108:109], v[120:121]
	v_fmac_f32_e32 v105, v118, v118
	v_fmac_f32_e32 v120, v3, v121
	v_pk_mul_f32 v[146:147], v[108:109], v[114:115]
	v_fmac_f32_e32 v105, v120, v120
	v_fmac_f32_e32 v146, v4, v147
	v_pk_mul_f32 v[148:149], v[108:109], v[116:117]
	v_fmac_f32_e32 v105, v146, v146
	v_fmac_f32_e32 v148, v5, v149
	v_pk_mul_f32 v[142:143], v[108:109], v[142:143]
	v_lshlrev_b32_e32 v138, 16, v51
	v_fmac_f32_e32 v105, v148, v148
	v_fmac_f32_e32 v142, v18, v143
	v_pk_mul_f32 v[144:145], v[108:109], v[144:145]
	v_and_b32_e32 v140, 0xffff0000, v51
	v_fmac_f32_e32 v105, v142, v142
	v_fmac_f32_e32 v144, v19, v145
	v_pk_mul_f32 v[138:139], v[108:109], v[138:139]
	v_lshlrev_b32_e32 v134, 16, v52
	v_fmac_f32_e32 v105, v144, v144
	v_fmac_f32_e32 v138, v20, v139
	v_pk_mul_f32 v[140:141], v[108:109], v[140:141]
	v_and_b32_e32 v136, 0xffff0000, v52
	v_fmac_f32_e32 v105, v138, v138
	v_fmac_f32_e32 v140, v21, v141
	v_pk_mul_f32 v[134:135], v[108:109], v[134:135]
	v_lshlrev_b32_e32 v130, 16, v53
	v_fmac_f32_e32 v105, v140, v140
	v_fmac_f32_e32 v134, v10, v135
	v_pk_mul_f32 v[136:137], v[108:109], v[136:137]
	v_and_b32_e32 v132, 0xffff0000, v53
	v_fmac_f32_e32 v105, v134, v134
	v_fmac_f32_e32 v136, v11, v137
	v_pk_mul_f32 v[130:131], v[108:109], v[130:131]
	v_fmac_f32_e32 v105, v136, v136
	v_fmac_f32_e32 v130, v12, v131
	v_pk_mul_f32 v[108:109], v[108:109], v[132:133]
	v_fmac_f32_e32 v105, v130, v130
	v_fmac_f32_e32 v108, v13, v109
	v_fmac_f32_e32 v105, v108, v108
	v_lshl_add_u64 v[132:133], s[14:15], 0, v[94:95]
	s_nop 0
	v_add_f32_dpp v105, v105, v105 quad_perm:[1,0,3,2] row_mask:0xf bank_mask:0xf bound_ctrl:1
	s_nop 1
	v_add_f32_dpp v105, v105, v105 quad_perm:[2,3,0,1] row_mask:0xf bank_mask:0xf bound_ctrl:1
	s_nop 1
	v_add_f32_dpp v105, v105, v105 row_half_mirror row_mask:0xf bank_mask:0xf bound_ctrl:1
	s_nop 1
	v_add_f32_dpp v105, v105, v105 row_mirror row_mask:0xf bank_mask:0xf bound_ctrl:1
	v_mov_b32_e32 v109, v105
	s_nop 1
	v_permlane16_swap_b32_e32 v105, v109
	v_add_f32_e32 v105, v105, v109
	v_mov_b32_e32 v109, v105
	s_nop 1
	v_permlane32_swap_b32_e32 v105, v109
	v_add_f32_e32 v105, v105, v109
	v_fmamk_f32 v105, v105, 0x3a800000, v201
	v_rsq_f32_e32 v105, v105
	s_nop 0
	v_mul_f32_e32 v109, v126, v105
	v_mul_f32_e32 v113, v128, v105
	v_cvt_pk_bf16_f32 v114, v109, v113
	v_mul_f32_e32 v109, v122, v105
	v_mul_f32_e32 v113, v124, v105
	v_cvt_pk_bf16_f32 v115, v109, v113
	v_mul_f32_e32 v109, v118, v105
	v_mul_f32_e32 v113, v120, v105
	v_cvt_pk_bf16_f32 v116, v109, v113
	v_mul_f32_e32 v109, v146, v105
	v_add_co_u32_e64 v118, s[2:3], s65, v132
	v_mul_f32_e32 v113, v148, v105
	v_cvt_pk_bf16_f32 v117, v109, v113
	s_nop 0
	v_addc_co_u32_e64 v119, s[2:3], 0, v133, s[2:3]
	v_mul_f32_e32 v109, v142, v105
	global_store_dwordx4 v[118:119], v[114:117], off
	v_mul_f32_e32 v113, v144, v105
	v_mul_f32_e32 v108, v108, v105
	v_cvt_pk_bf16_f32 v114, v109, v113
	v_mul_f32_e32 v109, v138, v105
	v_mul_f32_e32 v113, v140, v105
	v_cvt_pk_bf16_f32 v115, v109, v113
	v_mul_f32_e32 v109, v134, v105
	v_mul_f32_e32 v113, v136, v105
	v_cvt_pk_bf16_f32 v116, v109, v113
	v_mul_f32_e32 v109, v130, v105
	v_cvt_pk_bf16_f32 v117, v109, v108
	global_store_dwordx4 v[118:119], v[114:117], off offset:1024
	s_and_b64 exec, exec, s[0:1]
	s_cbranch_execz .LBB0_219
	v_lshl_add_u64 v[108:109], s[14:15], 0, v[92:93]
	global_store_dword v[108:109], v105, off

; __device__ __forceinline__ unsigned cvtpk(float lo, float hi) { unsigned r; asm volatile("v_cvt_pk_bf16_f32 %0, %1, %2" : "=v"(r) : "v"(lo), "v"(hi)); return r; }
; __device__ __forceinline__ float bf_lo(unsigned w) { return __uint_as_float(w << 16); }
; __device__ __forceinline__ float bf_hi(unsigned w) { return __uint_as_float(w & 0xffff0000u); }
; template <int MODE> __device__ __forceinline__ void norm_process(const NRow<MODE>& R, unsigned char* ws, float* out, int r, int lane, const float (&gp)[2][8]) {
;     float mf[2][8], xv[2][8]; float s = 0.f;
; #pragma unroll
;     for (int j = 0; j < 2; ++j) {
; #pragma unroll
;         for (int i = 0; i < 4; ++i) { mf[j][2 * i] = bf_lo(R.m[j][i]); mf[j][2 * i + 1] = bf_hi(R.m[j][i]); }
;         { const float ir = __builtin_amdgcn_rcpf(R.rs);
; #pragma unroll
;             for (int i = 0; i < 4; ++i) { xv[j][2 * i] = bf_lo(R.xh[j][i]) * ir; xv[j][2 * i + 1] = bf_hi(R.xh[j][i]) * ir; } }
; #pragma unroll
;         for (int i = 0; i < 8; ++i) s += mf[j][i] * mf[j][i]; }
;     const float rstd = __builtin_amdgcn_rsqf(wave_sum(s) * (1.f / DM) + RMS_EPS);
;     float s2 = 0.f;
; #pragma unroll
;     for (int j = 0; j < 2; ++j)
; #pragma unroll
;         for (int i = 0; i < 8; ++i) { xv[j][i] += mf[j][i] * rstd * gp[j][i]; s2 += xv[j][i] * xv[j][i]; }
;     if (MODE == 2) { float* orow = out + (size_t)r * DM + 8 * lane;
; #pragma unroll
;         for (int j = 0; j < 2; ++j) { __builtin_nontemporal_store((f32x4){xv[j][0], xv[j][1], xv[j][2], xv[j][3]}, (f32x4*)(orow + 512 * j)); __builtin_nontemporal_store((f32x4){xv[j][4], xv[j][5], xv[j][6], xv[j][7]}, (f32x4*)(orow + 512 * j + 4)); } }
;     else {
;         const float rstd2 = __builtin_amdgcn_rsqf(wave_sum(s2) * (1.f / DM) + RMS_EPS);
;         bf16* xo = (bf16*)(ws + WS_XN) + (size_t)r * DM + 8 * lane;
; #pragma unroll
;         for (int j = 0; j < 2; ++j) { u32x4 a;
; #pragma unroll
;             for (int i = 0; i < 4; ++i) a[i] = cvtpk(xv[j][2 * i] * rstd2, xv[j][2 * i + 1] * rstd2);
;             *(u32x4*)(xo + 512 * j) = a; }
;         if (lane == 0) ((float*)(ws + WS_RSTD))[r] = rstd2; }
; template <int MODE> __device__ __forceinline__ void norm_phase(unsigned char* ws, float* out, const float* gpost, const bf16* mbuf, int G) {
;     ...
;         if (r2 < MTOT) norm_process<MODE>(C, ws, out, r2, lane, gp);
.LBB0_221:
	s_or_b64 exec, exec, s[50:51]
	v_add_u32_e32 v105, s58, v112
	v_cmp_gt_i32_e64 s[2:3], s63, v105
	s_and_saveexec_b64 s[50:51], s[2:3]
	s_cbranch_execz .LBB0_224
	v_readlane_b32 s2, v246, 4
	s_nop 0
	s_cmp_lg_u32 s2, 0
	s_cbranch_scc0 .Lna_skip_3
	s_waitcnt vmcnt(24)
.Lna_skip_3:
	v_lshlrev_b32_e32 v127, 16, v54
	v_and_b32_e32 v129, 0xffff0000, v54
	v_mul_f32_e32 v105, v127, v127
	v_lshlrev_b32_e32 v123, 16, v55
	v_fmac_f32_e32 v105, v129, v129
	v_and_b32_e32 v125, 0xffff0000, v55
	v_fmac_f32_e32 v105, v123, v123
	v_lshlrev_b32_e32 v119, 16, v56
	v_fmac_f32_e32 v105, v125, v125
	v_and_b32_e32 v121, 0xffff0000, v56
	v_fmac_f32_e32 v105, v119, v119
	v_lshlrev_b32_e32 v115, 16, v57
	v_fmac_f32_e32 v105, v121, v121
	v_and_b32_e32 v117, 0xffff0000, v57
	v_fmac_f32_e32 v105, v115, v115
	v_lshlrev_b32_e32 v143, 16, v58
	v_fmac_f32_e32 v105, v117, v117
	v_and_b32_e32 v145, 0xffff0000, v58
	v_fmac_f32_e32 v105, v143, v143
	v_lshlrev_b32_e32 v139, 16, v59
	v_fmac_f32_e32 v105, v145, v145
	v_and_b32_e32 v141, 0xffff0000, v59
	v_fmac_f32_e32 v105, v139, v139
	v_lshlrev_b32_e32 v135, 16, v60
	v_fmac_f32_e32 v105, v141, v141
	v_and_b32_e32 v137, 0xffff0000, v60
	v_fmac_f32_e32 v105, v135, v135
	v_lshlrev_b32_e32 v131, 16, v61
	v_fmac_f32_e32 v105, v137, v137
	v_and_b32_e32 v133, 0xffff0000, v61
	v_fmac_f32_e32 v105, v131, v131
	v_fmac_f32_e32 v105, v133, v133
	v_rcp_f32_e32 v108, v110
	v_and_b32_e32 v128, 0xffff0000, v62
	v_add_f32_dpp v105, v105, v105 quad_perm:[1,0,3,2] row_mask:0xf bank_mask:0xf bound_ctrl:1
	v_lshlrev_b32_e32 v126, 16, v62
	v_lshlrev_b32_e32 v122, 16, v63
	v_add_f32_dpp v105, v105, v105 quad_perm:[2,3,0,1] row_mask:0xf bank_mask:0xf bound_ctrl:1
	v_and_b32_e32 v124, 0xffff0000, v63
	v_lshlrev_b32_e32 v118, 16, v64
	v_add_f32_dpp v105, v105, v105 row_half_mirror row_mask:0xf bank_mask:0xf bound_ctrl:1
	v_and_b32_e32 v120, 0xffff0000, v64
	v_lshlrev_b32_e32 v114, 16, v65
	v_add_f32_dpp v105, v105, v105 row_mirror row_mask:0xf bank_mask:0xf bound_ctrl:1
	v_mov_b32_e32 v109, v105
	s_nop 1
	v_permlane16_swap_b32_e32 v105, v109
	v_add_f32_e32 v105, v105, v109
	v_mov_b32_e32 v109, v105
	s_nop 1
	v_permlane32_swap_b32_e32 v105, v109
	v_add_f32_e32 v105, v105, v109
	v_fmamk_f32 v105, v105, 0x3a800000, v201
	v_rsq_f32_e32 v109, v105
	v_and_b32_e32 v116, 0xffff0000, v65
	v_lshlrev_b32_e32 v142, 16, v66
	v_and_b32_e32 v144, 0xffff0000, v66
	v_pk_mul_f32 v[128:129], v[108:109], v[128:129]
	v_pk_mul_f32 v[126:127], v[108:109], v[126:127]
	v_fmac_f32_e32 v128, v7, v129
	v_fmac_f32_e32 v126, v6, v127
	v_mul_f32_e32 v105, v128, v128
	v_pk_mul_f32 v[122:123], v[108:109], v[122:123]
	v_fmac_f32_e32 v105, v126, v126
	v_fmac_f32_e32 v122, v8, v123
	v_pk_mul_f32 v[124:125], v[108:109], v[124:125]
	v_fmac_f32_e32 v105, v122, v122
	v_fmac_f32_e32 v124, v9, v125
	v_pk_mul_f32 v[118:119], v[108:109], v[118:119]
	v_fmac_f32_e32 v105, v124, v124
	v_fmac_f32_e32 v118, v2, v119
	v_pk_mul_f32 v[120:121], v[108:109], v[120:121]
	v_fmac_f32_e32 v105, v118, v118
	v_fmac_f32_e32 v120, v3, v121
	v_pk_mul_f32 v[146:147], v[108:109], v[114:115]
	v_fmac_f32_e32 v105, v120, v120
	v_fmac_f32_e32 v146, v4, v147
	v_pk_mul_f32 v[148:149], v[108:109], v[116:117]
	v_fmac_f32_e32 v105, v146, v146
	v_fmac_f32_e32 v148, v5, v149
	v_pk_mul_f32 v[142:143], v[108:109], v[142:143]
	v_lshlrev_b32_e32 v138, 16, v67
	v_fmac_f32_e32 v105, v148, v148
	v_fmac_f32_e32 v142, v18, v143
	v_pk_mul_f32 v[144:145], v[108:109], v[144:145]
	v_and_b32_e32 v140, 0xffff0000, v67
	v_fmac_f32_e32 v105, v142, v142
	v_fmac_f32_e32 v144, v19, v145
	v_pk_mul_f32 v[138:139], v[108:109], v[138:139]
	v_lshlrev_b32_e32 v134, 16, v68
	v_fmac_f32_e32 v105, v144, v144
	v_fmac_f32_e32 v138, v20, v139
	v_pk_mul_f32 v[140:141], v[108:109], v[140:141]
	v_and_b32_e32 v136, 0xffff0000, v68
	v_fmac_f32_e32 v105, v138, v138
	v_fmac_f32_e32 v140, v21, v141
	v_pk_mul_f32 v[134:135], v[108:109], v[134:135]
	v_lshlrev_b32_e32 v130, 16, v69
	v_fmac_f32_e32 v105, v140, v140
	v_fmac_f32_e32 v134, v10, v135
	v_pk_mul_f32 v[136:137], v[108:109], v[136:137]
	v_and_b32_e32 v132, 0xffff0000, v69
	v_fmac_f32_e32 v105, v134, v134
	v_fmac_f32_e32 v136, v11, v137
	v_pk_mul_f32 v[130:131], v[108:109], v[130:131]
	v_fmac_f32_e32 v105, v136, v136
	v_fmac_f32_e32 v130, v12, v131
	v_pk_mul_f32 v[108:109], v[108:109], v[132:133]
	v_fmac_f32_e32 v105, v130, v130
	v_fmac_f32_e32 v108, v13, v109
	v_fmac_f32_e32 v105, v108, v108
	v_lshl_add_u64 v[132:133], s[14:15], 0, v[98:99]
	s_nop 0
	v_add_f32_dpp v105, v105, v105 quad_perm:[1,0,3,2] row_mask:0xf bank_mask:0xf bound_ctrl:1
	s_nop 1
	v_add_f32_dpp v105, v105, v105 quad_perm:[2,3,0,1] row_mask:0xf bank_mask:0xf bound_ctrl:1
	s_nop 1
	v_add_f32_dpp v105, v105, v105 row_half_mirror row_mask:0xf bank_mask:0xf bound_ctrl:1
	s_nop 1
	v_add_f32_dpp v105, v105, v105 row_mirror row_mask:0xf bank_mask:0xf bound_ctrl:1
	v_mov_b32_e32 v109, v105
	s_nop 1
	v_permlane16_swap_b32_e32 v105, v109
	v_add_f32_e32 v105, v105, v109
	v_mov_b32_e32 v109, v105
	s_nop 1
	v_permlane32_swap_b32_e32 v105, v109
	v_add_f32_e32 v105, v105, v109
	v_fmamk_f32 v105, v105, 0x3a800000, v201
	v_rsq_f32_e32 v105, v105
	s_nop 0
	v_mul_f32_e32 v109, v126, v105
	v_mul_f32_e32 v113, v128, v105
	v_cvt_pk_bf16_f32 v114, v109, v113
	v_mul_f32_e32 v109, v122, v105
	v_mul_f32_e32 v113, v124, v105
	v_cvt_pk_bf16_f32 v115, v109, v113
	v_mul_f32_e32 v109, v118, v105
	v_mul_f32_e32 v113, v120, v105
	v_cvt_pk_bf16_f32 v116, v109, v113
	v_mul_f32_e32 v109, v146, v105
	v_add_co_u32_e64 v118, s[2:3], s65, v132
	v_mul_f32_e32 v113, v148, v105
	v_cvt_pk_bf16_f32 v117, v109, v113
	s_nop 0
	v_addc_co_u32_e64 v119, s[2:3], 0, v133, s[2:3]
	v_mul_f32_e32 v109, v142, v105
	global_store_dwordx4 v[118:119], v[114:117], off
	v_mul_f32_e32 v113, v144, v105
	v_mul_f32_e32 v108, v108, v105
	v_cvt_pk_bf16_f32 v114, v109, v113
	v_mul_f32_e32 v109, v138, v105
	v_mul_f32_e32 v113, v140, v105
	v_cvt_pk_bf16_f32 v115, v109, v113
	v_mul_f32_e32 v109, v134, v105
	v_mul_f32_e32 v113, v136, v105
	v_cvt_pk_bf16_f32 v116, v109, v113
	v_mul_f32_e32 v109, v130, v105
	v_cvt_pk_bf16_f32 v117, v109, v108
	global_store_dwordx4 v[118:119], v[114:117], off offset:1024
	s_and_b64 exec, exec, s[0:1]
	s_cbranch_execz .LBB0_224
	v_lshl_add_u64 v[108:109], s[14:15], 0, v[96:97]
	global_store_dword v[108:109], v105, off

; __device__ __forceinline__ unsigned cvtpk(float lo, float hi) { unsigned r; asm volatile("v_cvt_pk_bf16_f32 %0, %1, %2" : "=v"(r) : "v"(lo), "v"(hi)); return r; }
; __device__ __forceinline__ float bf_lo(unsigned w) { return __uint_as_float(w << 16); }
; __device__ __forceinline__ float bf_hi(unsigned w) { return __uint_as_float(w & 0xffff0000u); }
; template <int MODE> __device__ __forceinline__ void norm_process(const NRow<MODE>& R, unsigned char* ws, float* out, int r, int lane, const float (&gp)[2][8]) {
;     float mf[2][8], xv[2][8]; float s = 0.f;
; #pragma unroll
;     for (int j = 0; j < 2; ++j) {
; #pragma unroll
;         for (int i = 0; i < 4; ++i) { mf[j][2 * i] = bf_lo(R.m[j][i]); mf[j][2 * i + 1] = bf_hi(R.m[j][i]); }
;         { const float ir = __builtin_amdgcn_rcpf(R.rs);
; #pragma unroll
;             for (int i = 0; i < 4; ++i) { xv[j][2 * i] = bf_lo(R.xh[j][i]) * ir; xv[j][2 * i + 1] = bf_hi(R.xh[j][i]) * ir; } }
; #pragma unroll
;         for (int i = 0; i < 8; ++i) s += mf[j][i] * mf[j][i]; }
;     const float rstd = __builtin_amdgcn_rsqf(wave_sum(s) * (1.f / DM) + RMS_EPS);
;     float s2 = 0.f;
; #pragma unroll
;     for (int j = 0; j < 2; ++j)
; #pragma unroll
;         for (int i = 0; i < 8; ++i) { xv[j][i] += mf[j][i] * rstd * gp[j][i]; s2 += xv[j][i] * xv[j][i]; }
;     if (MODE == 2) { float* orow = out + (size_t)r * DM + 8 * lane;
; #pragma unroll
;         for (int j = 0; j < 2; ++j) { __builtin_nontemporal_store((f32x4){xv[j][0], xv[j][1], xv[j][2], xv[j][3]}, (f32x4*)(orow + 512 * j)); __builtin_nontemporal_store((f32x4){xv[j][4], xv[j][5], xv[j][6], xv[j][7]}, (f32x4*)(orow + 512 * j + 4)); } }
;     else {
;         const float rstd2 = __builtin_amdgcn_rsqf(wave_sum(s2) * (1.f / DM) + RMS_EPS);
;         bf16* xo = (bf16*)(ws + WS_XN) + (size_t)r * DM + 8 * lane;
; #pragma unroll
;         for (int j = 0; j < 2; ++j) { u32x4 a;
; #pragma unroll
;             for (int i = 0; i < 4; ++i) a[i] = cvtpk(xv[j][2 * i] * rstd2, xv[j][2 * i + 1] * rstd2);
;             *(u32x4*)(xo + 512 * j) = a; }
;         if (lane == 0) ((float*)(ws + WS_RSTD))[r] = rstd2; }
; template <int MODE> __device__ __forceinline__ void norm_phase(unsigned char* ws, float* out, const float* gpost, const bf16* mbuf, int G) {
;     ...
;         if (r3 < MTOT) norm_process<MODE>(D, ws, out, r3, lane, gp);
.LBB0_226:
	s_or_b64 exec, exec, s[50:51]
	s_and_saveexec_b64 s[50:51], s[4:5]
	s_cbranch_execz .LBB0_209
	v_readlane_b32 s2, v246, 4
	s_nop 0
	s_cmp_lg_u32 s2, 0
	s_cbranch_scc0 .Lna_skip_4
	s_waitcnt vmcnt(24)
.Lna_skip_4:
	v_lshlrev_b32_e32 v125, 16, v70
	v_and_b32_e32 v127, 0xffff0000, v70
	v_mul_f32_e32 v105, v125, v125
	v_lshlrev_b32_e32 v121, 16, v71
	v_fmac_f32_e32 v105, v127, v127
	v_and_b32_e32 v123, 0xffff0000, v71
	v_fmac_f32_e32 v105, v121, v121
	v_lshlrev_b32_e32 v117, 16, v72
	v_fmac_f32_e32 v105, v123, v123
	v_and_b32_e32 v119, 0xffff0000, v72
	v_fmac_f32_e32 v105, v117, v117
	v_lshlrev_b32_e32 v113, 16, v73
	v_fmac_f32_e32 v105, v119, v119
	v_and_b32_e32 v115, 0xffff0000, v73
	v_fmac_f32_e32 v105, v113, v113
	v_lshlrev_b32_e32 v141, 16, v74
	v_fmac_f32_e32 v105, v115, v115
	v_and_b32_e32 v143, 0xffff0000, v74
	v_fmac_f32_e32 v105, v141, v141
	v_lshlrev_b32_e32 v137, 16, v75
	v_fmac_f32_e32 v105, v143, v143
	v_and_b32_e32 v139, 0xffff0000, v75
	v_fmac_f32_e32 v105, v137, v137
	v_lshlrev_b32_e32 v133, 16, v76
	v_fmac_f32_e32 v105, v139, v139
	v_and_b32_e32 v135, 0xffff0000, v76
	v_fmac_f32_e32 v105, v133, v133
	v_lshlrev_b32_e32 v129, 16, v77
	v_fmac_f32_e32 v105, v135, v135
	v_and_b32_e32 v131, 0xffff0000, v77
	v_fmac_f32_e32 v105, v129, v129
	v_fmac_f32_e32 v105, v131, v131
	v_rcp_f32_e32 v108, v111
	v_and_b32_e32 v126, 0xffff0000, v78
	v_add_f32_dpp v105, v105, v105 quad_perm:[1,0,3,2] row_mask:0xf bank_mask:0xf bound_ctrl:1
	v_lshlrev_b32_e32 v124, 16, v78
	v_lshlrev_b32_e32 v120, 16, v79
	v_add_f32_dpp v105, v105, v105 quad_perm:[2,3,0,1] row_mask:0xf bank_mask:0xf bound_ctrl:1
	v_and_b32_e32 v122, 0xffff0000, v79
	v_lshlrev_b32_e32 v116, 16, v80
	v_add_f32_dpp v105, v105, v105 row_half_mirror row_mask:0xf bank_mask:0xf bound_ctrl:1
	v_and_b32_e32 v118, 0xffff0000, v80
	v_lshlrev_b32_e32 v112, 16, v81
	v_add_f32_dpp v105, v105, v105 row_mirror row_mask:0xf bank_mask:0xf bound_ctrl:1
	v_mov_b32_e32 v109, v105
	s_nop 1
	v_permlane16_swap_b32_e32 v105, v109
	v_add_f32_e32 v105, v105, v109
	v_mov_b32_e32 v109, v105
	s_nop 1
	v_permlane32_swap_b32_e32 v105, v109
	v_add_f32_e32 v105, v105, v109
	v_fmamk_f32 v105, v105, 0x3a800000, v201
	v_rsq_f32_e32 v109, v105
	v_and_b32_e32 v114, 0xffff0000, v81
	v_lshlrev_b32_e32 v140, 16, v82
	v_and_b32_e32 v142, 0xffff0000, v82
	v_pk_mul_f32 v[126:127], v[108:109], v[126:127]
	v_pk_mul_f32 v[124:125], v[108:109], v[124:125]
	v_fmac_f32_e32 v126, v7, v127
	v_fmac_f32_e32 v124, v6, v125
	v_mul_f32_e32 v105, v126, v126
	v_pk_mul_f32 v[120:121], v[108:109], v[120:121]
	v_fmac_f32_e32 v105, v124, v124
	v_fmac_f32_e32 v120, v8, v121
	v_pk_mul_f32 v[122:123], v[108:109], v[122:123]
	v_fmac_f32_e32 v105, v120, v120
	v_fmac_f32_e32 v122, v9, v123
	v_pk_mul_f32 v[116:117], v[108:109], v[116:117]
	v_fmac_f32_e32 v105, v122, v122
	v_fmac_f32_e32 v116, v2, v117
	v_pk_mul_f32 v[118:119], v[108:109], v[118:119]
	v_fmac_f32_e32 v105, v116, v116
	v_fmac_f32_e32 v118, v3, v119
	v_pk_mul_f32 v[144:145], v[108:109], v[112:113]
	v_fmac_f32_e32 v105, v118, v118
	v_fmac_f32_e32 v144, v4, v145
	v_pk_mul_f32 v[146:147], v[108:109], v[114:115]
	v_fmac_f32_e32 v105, v144, v144
	v_fmac_f32_e32 v146, v5, v147
	v_pk_mul_f32 v[140:141], v[108:109], v[140:141]
	v_lshlrev_b32_e32 v136, 16, v83
	v_fmac_f32_e32 v105, v146, v146
	v_fmac_f32_e32 v140, v18, v141
	v_pk_mul_f32 v[142:143], v[108:109], v[142:143]
	v_and_b32_e32 v138, 0xffff0000, v83
	v_fmac_f32_e32 v105, v140, v140
	v_fmac_f32_e32 v142, v19, v143
	v_pk_mul_f32 v[136:137], v[108:109], v[136:137]
	v_lshlrev_b32_e32 v132, 16, v84
	v_fmac_f32_e32 v105, v142, v142
	v_fmac_f32_e32 v136, v20, v137
	v_pk_mul_f32 v[138:139], v[108:109], v[138:139]
	v_and_b32_e32 v134, 0xffff0000, v84
	v_fmac_f32_e32 v105, v136, v136
	v_fmac_f32_e32 v138, v21, v139
	v_pk_mul_f32 v[132:133], v[108:109], v[132:133]
	v_lshlrev_b32_e32 v128, 16, v85
	v_fmac_f32_e32 v105, v138, v138
	v_fmac_f32_e32 v132, v10, v133
	v_pk_mul_f32 v[134:135], v[108:109], v[134:135]
	v_and_b32_e32 v130, 0xffff0000, v85
	v_fmac_f32_e32 v105, v132, v132
	v_fmac_f32_e32 v134, v11, v135
	v_pk_mul_f32 v[128:129], v[108:109], v[128:129]
	v_fmac_f32_e32 v105, v134, v134
	v_fmac_f32_e32 v128, v12, v129
	v_pk_mul_f32 v[130:131], v[108:109], v[130:131]
	v_fmac_f32_e32 v105, v128, v128
	v_fmac_f32_e32 v130, v13, v131
	v_fmac_f32_e32 v105, v130, v130
	s_nop 1
	v_add_f32_dpp v105, v105, v105 quad_perm:[1,0,3,2] row_mask:0xf bank_mask:0xf bound_ctrl:1
	s_nop 1
	v_add_f32_dpp v105, v105, v105 quad_perm:[2,3,0,1] row_mask:0xf bank_mask:0xf bound_ctrl:1
	s_nop 1
	v_add_f32_dpp v105, v105, v105 row_half_mirror row_mask:0xf bank_mask:0xf bound_ctrl:1
	s_nop 1
	v_add_f32_dpp v105, v105, v105 row_mirror row_mask:0xf bank_mask:0xf bound_ctrl:1
	v_mov_b32_e32 v108, v105
	s_nop 1
	v_permlane16_swap_b32_e32 v105, v108
	v_add_f32_e32 v105, v105, v108
	v_mov_b32_e32 v108, v105
	s_nop 1
	v_permlane32_swap_b32_e32 v105, v108
	v_add_f32_e32 v105, v105, v108
	v_fmamk_f32 v105, v105, 0x3a800000, v201
	v_rsq_f32_e32 v105, v105
	s_nop 0
	v_mul_f32_e32 v108, v124, v105
	v_mul_f32_e32 v109, v126, v105
	v_cvt_pk_bf16_f32 v112, v108, v109
	v_mul_f32_e32 v108, v120, v105
	v_mul_f32_e32 v109, v122, v105
	v_cvt_pk_bf16_f32 v113, v108, v109
	v_mul_f32_e32 v108, v116, v105
	v_add_co_u32_e64 v116, s[2:3], s65, v106
	v_mul_f32_e32 v109, v118, v105
	v_cvt_pk_bf16_f32 v114, v108, v109
	v_mul_f32_e32 v108, v144, v105
	v_addc_co_u32_e64 v117, s[2:3], 0, v107, s[2:3]
	v_mul_f32_e32 v106, v140, v105
	v_mul_f32_e32 v107, v142, v105
	v_mul_f32_e32 v109, v146, v105
	v_cvt_pk_bf16_f32 v115, v108, v109
	global_store_dwordx4 v[116:117], v[112:115], off
	v_cvt_pk_bf16_f32 v106, v106, v107
	v_mul_f32_e32 v107, v136, v105
	v_mul_f32_e32 v108, v138, v105
	v_cvt_pk_bf16_f32 v107, v107, v108
	v_mul_f32_e32 v108, v132, v105
	v_mul_f32_e32 v109, v134, v105
	v_cvt_pk_bf16_f32 v108, v108, v109
	v_mul_f32_e32 v109, v128, v105
	v_mul_f32_e32 v112, v130, v105
	v_cvt_pk_bf16_f32 v109, v109, v112
	global_store_dwordx4 v[116:117], v[106:109], off offset:1024
	s_and_b64 exec, exec, s[0:1]
	s_cbranch_execz .LBB0_209
	v_lshl_add_u64 v[106:107], s[14:15], 0, v[100:101]
	global_store_dword v[106:107], v105, off
	s_branch .LBB0_209

; template <int MODE> __device__ __forceinline__ void norm_phase(unsigned char* ws, float* out, const float* gpost, const bf16* mbuf, int G) {
;     ...
;     NRow<MODE> A, B, C, D;
;     int r = gw;
;     if (r < MTOT) norm_load<MODE>(A, ws, mbuf, r, lane);
;     if (r + NGW < MTOT) norm_load<MODE>(B, ws, mbuf, r + NGW, lane);
;     if (r + 2 * NGW < MTOT) norm_load<MODE>(C, ws, mbuf, r + 2 * NGW, lane);
;     for (; r < MTOT; r += 4 * NGW) {
;         const int r1 = r + NGW, r2 = r1 + NGW, r3 = r2 + NGW, r4 = r3 + NGW, r5 = r4 + NGW, r6 = r5 + NGW;
;         if (r3 < MTOT) norm_load<MODE>(D, ws, mbuf, r3, lane);
.LBB0_372:
	s_or_b64 exec, exec, s[2:3]
	s_and_saveexec_b64 s[8:9], vcc
	s_cbranch_execz .LBB0_436
	v_readlane_b32 s0, v245, 27
	v_mov_b32_e32 v71, v0
	v_readlane_b32 s1, v245, 28
	v_lshl_add_u64 v[86:87], s[6:7], 0, v[70:71]
	v_readlane_b32 s2, v244, 15
	v_lshl_add_u64 v[14:15], s[0:1], 0, v[70:71]
	v_lshlrev_b32_e32 v70, 4, v73
	v_and_b32_e32 v73, 0x3f0, v70
	v_add_u32_e32 v70, s2, v72
	v_ashrrev_i32_e32 v71, 31, v70
	v_readlane_b32 s2, v244, 16
	v_lshl_add_u64 v[92:93], v[70:71], 2, v[182:183]
	v_lshlrev_b64 v[94:95], 11, v[70:71]
	v_add_u32_e32 v70, s2, v72
	v_ashrrev_i32_e32 v71, 31, v70
	v_readlane_b32 s2, v244, 17
	v_lshl_add_u64 v[96:97], v[70:71], 2, v[182:183]
	v_lshlrev_b64 v[98:99], 11, v[70:71]
	v_add_u32_e32 v70, s2, v72
	v_ashrrev_i32_e32 v71, 31, v70
	v_lshlrev_b64 v[90:91], 11, v[104:105]
	v_lshlrev_b64 v[102:103], 11, v[70:71]
	v_cmp_eq_u32_e64 s[0:1], 0, v74
	v_lshl_add_u64 v[88:89], v[104:105], 2, v[182:183]
	v_or_b32_e32 v90, v90, v73
	v_or_b32_e32 v94, v94, v73
	v_or_b32_e32 v98, v98, v73
	v_lshl_add_u64 v[100:101], v[70:71], 2, v[182:183]
	v_or_b32_e32 v102, v102, v73
	s_mov_b64 s[18:19], 0
	s_mov_b32 s2, 1
	s_nop 0
	v_writelane_b32 v246, s2, 3
	s_branch .LBB0_375
.LBB0_374:
	s_mov_b32 s2, 0
	s_nop 0
	v_writelane_b32 v246, s2, 3
	s_or_b64 exec, exec, s[28:29]
	s_and_b64 s[2:3], exec, vcc
	s_or_b64 s[18:19], s[2:3], s[18:19]
	v_lshl_add_u64 v[88:89], v[88:89], 0, s[96:97]
	v_lshl_add_u64 v[90:91], v[90:91], 0, s[98:99]
	v_lshl_add_u64 v[92:93], v[92:93], 0, s[96:97]
	v_lshl_add_u64 v[94:95], v[94:95], 0, s[98:99]
	v_lshl_add_u64 v[96:97], v[96:97], 0, s[96:97]
	v_lshl_add_u64 v[98:99], v[98:99], 0, s[98:99]
	v_lshl_add_u64 v[100:101], v[100:101], 0, s[96:97]
	v_lshl_add_u64 v[102:103], v[102:103], 0, s[98:99]
	s_andn2_b64 exec, exec, s[18:19]
	s_cbranch_execz .LBB0_436
.LBB0_375:
	v_mov_b32_e32 v112, v104
	s_mul_i32 s2, s33, 48
	v_add_u32_e32 v247, s2, v112
	v_cmp_gt_i32_e32 vcc, s63, v247
	v_readlane_b32 s2, v246, 3
	s_or_b32 s3, vcc_lo, vcc_hi
	s_cmp_eq_u32 s2, 0
	s_cselect_b32 s3, s3, 0
	s_nop 0
	v_writelane_b32 v246, s3, 4
	v_add_u32_e32 v104, s17, v112
	v_cmp_gt_i32_e64 s[4:5], s63, v104
	v_lshl_add_u64 v[106:107], s[14:15], 0, v[102:103]
	s_and_saveexec_b64 s[2:3], s[4:5]
	s_cbranch_execz .LBB0_377
	v_add_co_u32_e32 v74, vcc, 0x33000000, v106
	v_lshl_add_u64 v[104:105], s[14:15], 0, v[100:101]
	s_nop 0
	v_addc_co_u32_e32 v75, vcc, 0, v107, vcc
	v_add_co_u32_e32 v82, vcc, 0x6000000, v106
	global_load_dwordx4 v[70:73], v[74:75], off nt
	s_nop 0
	global_load_dwordx4 v[74:77], v[74:75], off offset:1024 nt
	v_addc_co_u32_e32 v83, vcc, 0, v107, vcc
	global_load_dwordx4 v[78:81], v[82:83], off
	s_nop 0
	global_load_dwordx4 v[82:85], v[82:83], off offset:1024
	s_nop 0
	global_load_dword v111, v[104:105], off

; template <int MODE> __device__ __forceinline__ void norm_phase(unsigned char* ws, float* out, const float* gpost, const bf16* mbuf, int G) {
;     ...
;         if (r1 < MTOT) norm_process<MODE>(B, ws, out, r1, lane, gp);
.LBB0_381:
	s_or_b64 exec, exec, s[28:29]
	v_add_u32_e32 v105, s57, v112
	v_cmp_gt_i32_e64 s[2:3], s63, v105
	s_and_saveexec_b64 s[28:29], s[2:3]
	s_cbranch_execz .LBB0_384
	v_readlane_b32 s2, v246, 4
	s_nop 0
	s_cmp_lg_u32 s2, 0
	s_cbranch_scc0 .Lnb_skip_2
	s_waitcnt vmcnt(24)

; template <int MODE> __device__ __forceinline__ void norm_phase(unsigned char* ws, float* out, const float* gpost, const bf16* mbuf, int G) {
;     ...
;         if (r2 < MTOT) norm_process<MODE>(C, ws, out, r2, lane, gp);
.LBB0_386:
	s_or_b64 exec, exec, s[28:29]
	v_add_u32_e32 v105, s58, v112
	v_cmp_gt_i32_e64 s[2:3], s63, v105
	s_and_saveexec_b64 s[28:29], s[2:3]
	s_cbranch_execz .LBB0_389
	v_readlane_b32 s2, v246, 4
	s_nop 0
	s_cmp_lg_u32 s2, 0
	s_cbranch_scc0 .Lnb_skip_3
	s_waitcnt vmcnt(24)

; template <int MODE> __device__ __forceinline__ void norm_phase(unsigned char* ws, float* out, const float* gpost, const bf16* mbuf, int G) {
;     ...
;         if (r3 < MTOT) norm_process<MODE>(D, ws, out, r3, lane, gp);
.LBB0_391:
	s_or_b64 exec, exec, s[28:29]
	s_and_saveexec_b64 s[28:29], s[4:5]
	s_cbranch_execz .LBB0_374
	v_readlane_b32 s2, v246, 4
	s_nop 0
	s_cmp_lg_u32 s2, 0
	s_cbranch_scc0 .Lnb_skip_4
	s_waitcnt vmcnt(24)
